# early-inv barrier + non-leader blocks poll the top-level generation word directly (one hop less)
# speedup vs baseline: 1.0201x; 1.0019x over previous
.LBB0_646:
	s_or_b64 exec, exec, s[4:5]
	v_cvt_f32_u32_e32 v5, v3
	s_waitcnt vmcnt(0)
	v_readfirstlane_b32 s2, v4
	v_sub_u32_e32 v4, 0, v3
	v_rcp_iflag_f32_e32 v5, v5
	v_add_u32_e32 v6, s2, v0
	v_mul_f32_e32 v5, 0x4f7ffffe, v5
	v_cvt_u32_f32_e32 v5, v5
	v_mul_lo_u32 v0, v4, v5
	v_mul_hi_u32 v0, v5, v0
	v_add_u32_e32 v0, v5, v0
	v_mul_hi_u32 v0, v6, v0
	v_mul_lo_u32 v4, v0, v3
	v_sub_u32_e32 v4, v6, v4
	v_add_u32_e32 v5, 1, v0
	v_cmp_ge_u32_e32 vcc, v4, v3
	s_nop 1
	v_cndmask_b32_e32 v0, v0, v5, vcc
	v_sub_u32_e32 v5, v4, v3
	v_cndmask_b32_e32 v4, v4, v5, vcc
	v_add_u32_e32 v5, 1, v0
	v_cmp_ge_u32_e32 vcc, v4, v3
	v_add_u32_e32 v4, 1, v6
	s_nop 0
	v_cndmask_b32_e32 v0, v0, v5, vcc
	v_mul_lo_u32 v5, v3, v0
	v_add_u32_e32 v3, v5, v3
	v_cmp_ne_u32_e32 vcc, v4, v3
	s_and_saveexec_b64 s[2:3], vcc
	s_xor_b64 s[4:5], exec, s[2:3]
	s_cbranch_execz .LBB0_660
	v_readlane_b32 s2, v247, 19
	v_readlane_b32 s3, v247, 20
	s_waitcnt lgkmcnt(0)
	s_nop 3
	buffer_inv sc1
	global_load_dword v2, v1, s[2:3] sc1
	s_waitcnt vmcnt(0)
	v_cmp_eq_u32_e32 vcc, v2, v0
	s_and_saveexec_b64 s[6:7], vcc
	s_cbranch_execz .LBB0_659
	s_mov_b32 s2, 1
	s_mov_b64 s[8:9], 0
	s_branch .LBB0_650
